# P3 diff-attention loops: next K/V tile requested right after the LDS stores are issued (before the barrier)
# speedup vs baseline: 1.0059x; 1.0059x over previous
.LBB0_459:
	s_add_i32 s15, s13, 9
	v_add_u32_e32 v66, v187, v174
	s_cmp_ge_u32 s15, s10
	s_waitcnt vmcnt(63) expcnt(7) lgkmcnt(15)
	s_barrier
	s_waitcnt vmcnt(7)
	ds_write_b128 v66, v[114:117]
	s_waitcnt vmcnt(6)
	ds_write_b128 v188, v[118:121] offset:17408
	s_waitcnt vmcnt(5)
	ds_write_b128 v66, v[122:125] offset:4352
	s_waitcnt vmcnt(4)
	ds_write_b128 v188, v[126:129] offset:22016
	s_waitcnt vmcnt(3)
	ds_write_b128 v66, v[130:133] offset:8704
	s_waitcnt vmcnt(2)
	ds_write_b128 v188, v[134:137] offset:26624
	s_waitcnt vmcnt(1)
	ds_write_b128 v66, v[138:141] offset:13056
	s_waitcnt vmcnt(0)
	ds_write_b128 v188, v[142:145] offset:31232
	s_cbranch_scc1 .Lp3e_461
	s_sub_i32 s15, s12, 48
	v_mad_u64_u32 v[66:67], s[16:17], s15, v182, v[176:177]
	v_mad_u64_u32 v[68:69], s[16:17], s15, v182, v[178:179]
	s_sub_i32 s15, s12, 32
	global_load_dwordx4 v[114:117], v[66:67], off offset:2048
	global_load_dwordx4 v[118:121], v[68:69], off
	v_mad_u64_u32 v[66:67], s[16:17], s15, v182, v[176:177]
	v_mad_u64_u32 v[68:69], s[16:17], s15, v182, v[178:179]
	s_add_i32 s15, s12, -16
	global_load_dwordx4 v[122:125], v[66:67], off offset:2048
	global_load_dwordx4 v[126:129], v[68:69], off
	v_mad_u64_u32 v[66:67], s[16:17], s15, v182, v[176:177]
	v_mad_u64_u32 v[68:69], s[16:17], s15, v182, v[178:179]
	global_load_dwordx4 v[130:133], v[66:67], off offset:2048
	global_load_dwordx4 v[134:137], v[68:69], off
	v_mad_u64_u32 v[66:67], s[16:17], s12, v182, v[176:177]
	v_mad_u64_u32 v[68:69], s[16:17], s12, v182, v[178:179]
	global_load_dwordx4 v[138:141], v[66:67], off offset:2048
	global_load_dwordx4 v[142:145], v[68:69], off
.Lp3e_461:
	s_waitcnt lgkmcnt(0)
	s_barrier

.LBB0_525:
	s_add_i32 s14, s13, 18
	v_add_u32_e32 v66, v0, v162
	s_cmp_ge_u32 s14, s10
	s_waitcnt vmcnt(63) expcnt(7) lgkmcnt(15)
	s_barrier
	s_waitcnt vmcnt(7)
	ds_write_b128 v66, v[114:117]
	s_waitcnt vmcnt(6)
	ds_write_b128 v177, v[118:121] offset:17408
	s_waitcnt vmcnt(5)
	ds_write_b128 v66, v[122:125] offset:4352
	s_waitcnt vmcnt(4)
	ds_write_b128 v177, v[126:129] offset:22016
	s_waitcnt vmcnt(3)
	ds_write_b128 v66, v[130:133] offset:8704
	s_waitcnt vmcnt(2)
	ds_write_b128 v177, v[134:137] offset:26624
	s_waitcnt vmcnt(1)
	ds_write_b128 v66, v[138:141] offset:13056
	s_waitcnt vmcnt(0)
	ds_write_b128 v177, v[142:145] offset:31232
	s_cbranch_scc1 .Lp3e_527
	v_add_co_u32_e32 v66, vcc, 0xfff04000, v164
	s_nop 1
	v_addc_co_u32_e32 v67, vcc, -1, v165, vcc
	global_load_dwordx4 v[114:117], v[66:67], off offset:-2048
	global_load_dwordx4 v[118:121], v[66:67], off
	v_add_co_u32_e32 v66, vcc, 0xfff58000, v164
	s_nop 1
	v_addc_co_u32_e32 v67, vcc, -1, v165, vcc
	global_load_dwordx4 v[122:125], v[66:67], off offset:-2048
	global_load_dwordx4 v[126:129], v[66:67], off
	v_add_co_u32_e32 v66, vcc, 0xfffac000, v164
	s_nop 1
	v_addc_co_u32_e32 v67, vcc, -1, v165, vcc
	global_load_dwordx4 v[130:133], v[66:67], off offset:-2048
	global_load_dwordx4 v[134:137], v[66:67], off
	global_load_dwordx4 v[138:141], v[164:165], off offset:-2048
	global_load_dwordx4 v[142:145], v[164:165], off

.LBB0_536:
	v_add_u32_e32 v66, v185, v184
	s_cmp_gt_u32 s13, 15
	s_waitcnt vmcnt(63) expcnt(7) lgkmcnt(15)
	s_barrier
	s_waitcnt vmcnt(7)
	ds_write_b128 v66, v[114:117]
	s_waitcnt vmcnt(6)
	ds_write_b128 v186, v[118:121] offset:17408
	s_waitcnt vmcnt(5)
	ds_write_b128 v66, v[122:125] offset:4352
	s_waitcnt vmcnt(4)
	ds_write_b128 v186, v[126:129] offset:22016
	s_waitcnt vmcnt(3)
	ds_write_b128 v66, v[130:133] offset:8704
	s_waitcnt vmcnt(2)
	ds_write_b128 v186, v[134:137] offset:26624
	s_waitcnt vmcnt(1)
	ds_write_b128 v66, v[138:141] offset:13056
	s_waitcnt vmcnt(0)
	ds_write_b128 v186, v[142:145] offset:31232
	s_cbranch_scc1 .Lp3e_538
	v_lshl_add_u64 v[66:67], v[174:175], 0, s[10:11]
	v_add_co_u32_e32 v68, vcc, 0x19f28000, v66
	s_nop 1
	v_addc_co_u32_e32 v69, vcc, 0, v67, vcc
	v_add_co_u32_e32 v70, vcc, 0x1b028000, v66
	s_nop 1
	v_addc_co_u32_e32 v71, vcc, 0, v67, vcc
	global_load_dwordx4 v[114:117], v[68:69], off
	global_load_dwordx4 v[118:121], v[70:71], off
	v_add_co_u32_e32 v68, vcc, 0x19f30000, v66
	s_nop 1
	v_addc_co_u32_e32 v69, vcc, 0, v67, vcc
	v_add_co_u32_e32 v70, vcc, 0x1b030000, v66
	s_nop 1
	v_addc_co_u32_e32 v71, vcc, 0, v67, vcc
	global_load_dwordx4 v[122:125], v[68:69], off
	global_load_dwordx4 v[126:129], v[70:71], off
	v_add_co_u32_e32 v68, vcc, 0x19f38000, v66
	s_nop 1
	v_addc_co_u32_e32 v69, vcc, 0, v67, vcc
	v_add_co_u32_e32 v70, vcc, 0x1b038000, v66
	s_nop 1
	v_addc_co_u32_e32 v71, vcc, 0, v67, vcc
	global_load_dwordx4 v[130:133], v[68:69], off
	global_load_dwordx4 v[134:137], v[70:71], off
	v_add_co_u32_e32 v68, vcc, 0x19f40000, v66
	s_nop 1
	v_addc_co_u32_e32 v69, vcc, 0, v67, vcc
	v_add_co_u32_e32 v66, vcc, 0x1b040000, v66
	s_nop 1
	v_addc_co_u32_e32 v67, vcc, 0, v67, vcc
	global_load_dwordx4 v[138:141], v[68:69], off
	global_load_dwordx4 v[142:145], v[66:67], off

.LBB0_547:
	s_add_i32 s15, s14, 33
	v_add_u32_e32 v66, v187, v174
	s_cmp_ge_u32 s15, s10
	s_waitcnt vmcnt(63) expcnt(7) lgkmcnt(15)
	s_barrier
	s_waitcnt vmcnt(7)
	ds_write_b128 v66, v[114:117]
	s_waitcnt vmcnt(6)
	ds_write_b128 v188, v[118:121] offset:17408
	s_waitcnt vmcnt(5)
	ds_write_b128 v66, v[122:125] offset:4352
	s_waitcnt vmcnt(4)
	ds_write_b128 v188, v[126:129] offset:22016
	s_waitcnt vmcnt(3)
	ds_write_b128 v66, v[130:133] offset:8704
	s_waitcnt vmcnt(2)
	ds_write_b128 v188, v[134:137] offset:26624
	s_waitcnt vmcnt(1)
	ds_write_b128 v66, v[138:141] offset:13056
	s_waitcnt vmcnt(0)
	ds_write_b128 v188, v[142:145] offset:31232
	s_cbranch_scc1 .Lp3e_549
	s_sub_i32 s15, s13, 48
	v_mad_u64_u32 v[66:67], s[16:17], s15, v182, v[176:177]
	v_mad_u64_u32 v[68:69], s[16:17], s15, v182, v[178:179]
	s_sub_i32 s15, s13, 32
	global_load_dwordx4 v[114:117], v[66:67], off offset:2048
	global_load_dwordx4 v[118:121], v[68:69], off
	v_mad_u64_u32 v[66:67], s[16:17], s15, v182, v[176:177]
	v_mad_u64_u32 v[68:69], s[16:17], s15, v182, v[178:179]
	s_add_i32 s15, s13, -16
	global_load_dwordx4 v[122:125], v[66:67], off offset:2048
	global_load_dwordx4 v[126:129], v[68:69], off
	v_mad_u64_u32 v[66:67], s[16:17], s15, v182, v[176:177]
	v_mad_u64_u32 v[68:69], s[16:17], s15, v182, v[178:179]
	global_load_dwordx4 v[130:133], v[66:67], off offset:2048
	global_load_dwordx4 v[134:137], v[68:69], off
	v_mad_u64_u32 v[66:67], s[16:17], s13, v182, v[176:177]
	v_mad_u64_u32 v[68:69], s[16:17], s13, v182, v[178:179]
	global_load_dwordx4 v[138:141], v[66:67], off offset:2048
	global_load_dwordx4 v[142:145], v[68:69], off
